# v21 + attention K-tile XOR swizzle widened to (row&15)<<4 for conflict-free ds_read_b128 QK reads
# speedup vs baseline: 1.0008x; 1.0005x over previous
.LBB0_303:
	s_or_b64 exec, exec, s[8:9]
	v_readlane_b32 s8, v255, 24
	s_waitcnt lgkmcnt(0)
	s_barrier
	v_mov_b32_e32 v1, s8
	ds_read_b32 v1, v1
	s_mov_b64 s[8:9], -1
	s_waitcnt lgkmcnt(0)
	s_barrier
	v_readfirstlane_b32 s10, v1
	s_cmpk_gt_i32 s10, 0x4f
	s_cbranch_scc1 .LBB0_298
	s_mul_hi_i32 s8, s10, 0x66666667
	s_lshr_b32 s9, s8, 31
	s_lshr_b32 s8, s8, 2
	s_add_i32 s8, s8, s9
	s_mul_i32 s8, s8, 10
	s_sub_i32 s8, s10, s8
	s_lshl_b32 s8, s8, 3
	s_or_b32 s8, s8, s81
	s_mul_hi_i32 s9, s8, 0x66666667
	s_lshr_b32 s11, s9, 31
	s_ashr_i32 s9, s9, 1
	s_add_i32 s18, s9, s11
	s_mul_i32 s9, s18, 5
	s_sub_i32 s13, s8, s9
	s_add_i32 s8, s13, 1
	v_cvt_f32_i32_e32 v1, s8
	s_mov_b32 s12, 0x40a00000
	s_mul_hi_i32 s10, s10, 0x99999999
	s_lshr_b32 s11, s10, 31
	v_mul_f32_e32 v1, 0xc1000000, v1
	v_div_scale_f32 v2, s[8:9], s12, s12, v1
	v_rcp_f32_e32 v3, v2
	s_mov_b32 s9, 0xc2fc0000
	s_ashr_i32 s8, s10, 2
	s_add_i32 s8, s8, s11
	v_fma_f32 v4, -v2, v3, 1.0
	v_fmac_f32_e32 v3, v4, v3
	v_div_scale_f32 v4, vcc, v1, s12, v1
	v_mul_f32_e32 v5, v4, v3
	v_fma_f32 v6, -v2, v5, v4
	v_fmac_f32_e32 v5, v6, v3
	v_fma_f32 v2, -v2, v5, v4
	v_div_fmas_f32 v2, v2, v3, v5
	v_div_fixup_f32 v1, v2, s12, v1
	v_cmp_gt_f32_e32 vcc, s9, v1
	v_mov_b32_e32 v2, 0x42800000
	s_add_i32 s20, s8, 7
	v_cndmask_b32_e32 v2, 0, v2, vcc
	v_add_f32_e32 v1, v1, v2
	v_exp_f32_e32 v1, v1
	s_and_b64 s[10:11], vcc, exec
	s_cselect_b32 s9, 0xffffffc0, 0
	s_lshl_b32 s10, s20, 8
	v_ldexp_f32 v1, v1, s9
	v_mul_f32_e32 v188, 0x3fb8aa3b, v1
	v_mov_b32_e32 v1, v0
	s_ashr_i32 s19, s18, 31
	v_readfirstlane_b32 s21, v1
	v_lshlrev_b32_e32 v7, 3, v1
	s_ashr_i32 s22, s21, 6
	v_ashrrev_i32_e32 v37, 4, v1
	v_and_b32_e32 v2, 0x78, v7
	s_lshl_b32 s9, s22, 5
	s_lshl_b32 s52, s13, 7
	s_lshl_b32 s13, s13, 23
	v_lshlrev_b32_e32 v34, 1, v2
	v_and_b32_e32 v2, 0xfffff0, v37
	v_lshlrev_b32_e32 v3, 1, v37
	s_add_i32 s53, s9, s10
	s_lshl_b64 s[54:55], s[18:19], 11
	s_add_i32 s10, s13, 0xb800000
	v_readlane_b32 s28, v254, 52
	v_and_or_b32 v2, v3, 8, v2
	v_readlane_b32 s29, v254, 53
	s_add_u32 s23, s28, s10
	v_lshrrev_b32_e32 v3, 1, v37
	v_lshrrev_b32_e32 v2, 1, v2
	v_bfe_u32 v4, v7, 5, 2
	v_and_b32_e32 v5, 3, v37
	s_addc_u32 s24, s29, 0
	s_lshl_b64 s[10:11], s[18:19], 19
	v_or_b32_e32 v2, v2, v4
	v_and_or_b32 v3, v3, 4, v5
	s_add_u32 s56, s23, s10
	v_lshlrev_b32_e32 v2, 9, v2
	v_lshlrev_b32_e32 v3, 6, v3
	v_and_b32_e32 v5, 48, v34
	s_addc_u32 s57, s24, s11
	s_add_i32 s18, s13, 0xe000000
	v_or3_b32 v224, v2, v3, v5
	v_add_u32_e32 v2, 32, v37
	s_add_u32 s18, s28, s18
	v_and_b32_e32 v8, 0xfffff0, v2
	v_lshlrev_b32_e32 v2, 1, v2
	s_addc_u32 s19, s29, 0
	v_and_or_b32 v2, v2, 8, v8
	s_add_u32 s18, s18, s10
	v_lshrrev_b32_e32 v2, 1, v2
	s_addc_u32 s19, s19, s11
	v_or_b32_e32 v2, v2, v4
	s_lshl_b32 s11, s22, 12
	v_lshlrev_b32_e32 v2, 9, v2
	s_lshl_b32 s82, s20, 2
	s_add_i32 s84, s11, 0
	s_lshl_b32 s11, s22, 2
	v_or3_b32 v225, v2, v3, v5
	v_lshlrev_b32_e32 v2, 1, v1
	s_add_i32 s85, s11, 0
	v_ashrrev_i32_e32 v44, 3, v1
	s_or_b32 s11, s82, 3
	v_and_b32_e32 v9, 32, v2
	s_and_b32 s10, s21, 0x3fffffc0
	v_lshlrev_b32_e32 v2, 4, v44
	s_lshl_b32 s20, s11, 6
	s_lshl_b32 s10, s10, 2
	v_and_b32_e32 v228, 0xf0, v2
	v_add_u32_e32 v2, s20, v37
	s_add_i32 s33, s10, 0
	s_ashr_i32 s10, s53, 6
	v_ashrrev_i32_e32 v3, 31, v2
	s_add_i32 s33, s33, 0x10200
	s_add_i32 s83, s82, 4
	s_add_i32 s84, s84, 0x10ac0
	s_add_i32 s85, s85, 0x10a00
	v_lshlrev_b64 v[2:3], 8, v[2:3]
	s_sub_i32 s86, s11, s10
	v_and_b32_e32 v6, 63, v1
	v_lshl_add_u64 v[2:3], s[18:19], 0, v[2:3]
	s_cmp_gt_i32 s86, 0
	s_movk_i32 s11, 0x118
	v_lshlrev_b32_e32 v226, 4, v6
	v_lshl_add_u64 v[192:193], v[2:3], 0, v[34:35]
	s_cselect_b64 s[58:59], -1, 0
	v_and_or_b32 v2, v7, s11, v9
	s_and_b32 s11, s53, 0xffffffc0
	v_and_b32_e32 v8, 0xc0, v226
	v_lshl_add_u64 v[196:197], s[18:19], 0, v[34:35]
	s_sub_i32 s18, s11, 64
	v_lshlrev_b32_e32 v3, 4, v1
	v_add3_u32 v233, v8, 0, v2
	v_add_u32_e32 v2, s18, v37
	v_and_b32_e32 v185, 31, v1
	v_bfe_u32 v189, v1, 5, 1
	v_and_b32_e32 v230, 0xf0, v3
	v_ashrrev_i32_e32 v3, 31, v2
	v_or_b32_e32 v223, s53, v185
	v_add_u32_e32 v4, s20, v44
	v_lshlrev_b64 v[2:3], 8, v[2:3]
	v_lshlrev_b32_e32 v45, 2, v189
	v_ashrrev_i32_e32 v5, 31, v4
	v_lshl_add_u64 v[202:203], v[196:197], 0, v[2:3]
	v_sub_u32_e32 v2, v223, v45
	v_lshlrev_b64 v[4:5], 8, v[4:5]
	v_subrev_u32_e32 v2, s11, v2
	v_lshl_add_u64 v[190:191], s[56:57], 0, v[4:5]
	v_add_u32_e32 v4, s18, v44
	s_lshl_b32 s18, s86, 14
	v_cvt_f32_i32_e32 v18, v2
	v_lshl_add_u32 v231, v185, 8, 0
	s_and_b32 s18, s18, 0x4000
	v_add_u32_e32 v235, s18, v231
	v_add_u32_e32 v236, s18, v233
	s_xor_b32 s88, s18, 0x4000
	s_mov_b32 s18, 0xc1000000
	v_ashrrev_i32_e32 v5, 31, v4
	s_mov_b32 s19, 0xc1100000
	v_lshlrev_b64 v[200:201], 8, v[4:5]
	v_pk_add_f32 v[4:5], v[18:19], s[18:19] op_sel_hi:[0,1]
	s_mov_b32 s18, 0xc1200000
	s_mov_b32 s19, 0xc1300000
	v_cmp_eq_u32_e64 s[38:39], 0, v6
	v_and_b32_e32 v227, 56, v7
	v_cmp_gt_u32_e64 s[40:41], 32, v6
	v_pk_add_f32 v[6:7], v[18:19], s[18:19] op_sel_hi:[0,1]
	s_mov_b32 s18, 0xc1800000
	s_mov_b32 s19, 0xc1880000
	v_pk_add_f32 v[8:9], v[18:19], s[18:19] op_sel_hi:[0,1]
	s_mov_b32 s18, 0xc1900000
	s_mov_b32 s19, 0xc1980000
	v_pk_add_f32 v[10:11], v[18:19], s[18:19] op_sel_hi:[0,1]
	s_mov_b32 s18, 0xc1c00000
	s_mov_b32 s19, 0xc1c80000
	v_pk_add_f32 v[12:13], v[18:19], s[18:19] op_sel_hi:[0,1]
	s_mov_b32 s18, 0xc1d00000
	s_add_i32 s87, s86, 1
	s_add_i32 s89, s88, 0
	s_add_i32 s13, s13, 0x9000000
	s_mov_b32 s19, 0xc1d80000
	s_add_u32 s60, s28, s13
	v_add_f32_e32 v16, -1.0, v18
	v_pk_add_f32 v[2:3], v[18:19], s[96:97] op_sel_hi:[0,1]
	v_pk_add_f32 v[14:15], v[18:19], s[18:19] op_sel_hi:[0,1]
	s_mov_b32 s18, 0xc2680000
	s_addc_u32 s61, s29, 0
	v_and_b32_e32 v34, 32, v1
	v_and_b32_e32 v20, 0x7fffffff, v18
	v_and_b32_e32 v21, 0x7fffffff, v16
	v_and_b32_e32 v3, 0x7fffffff, v3
	v_and_b32_e32 v2, 0x7fffffff, v2
	v_and_b32_e32 v5, 0x7fffffff, v5
	v_and_b32_e32 v4, 0x7fffffff, v4
	v_and_b32_e32 v7, 0x7fffffff, v7
	v_and_b32_e32 v6, 0x7fffffff, v6
	v_and_b32_e32 v9, 0x7fffffff, v9
	v_and_b32_e32 v8, 0x7fffffff, v8
	v_and_b32_e32 v11, 0x7fffffff, v11
	v_and_b32_e32 v10, 0x7fffffff, v10
	v_and_b32_e32 v13, 0x7fffffff, v13
	v_and_b32_e32 v12, 0x7fffffff, v12
	v_and_b32_e32 v15, 0x7fffffff, v15
	v_and_b32_e32 v14, 0x7fffffff, v14
	s_mov_b32 s19, 0xc26c0000
	s_lshl_b32 s13, s8, 8
	v_lshl_add_u64 v[206:207], s[44:45], 0, v[34:35]
	v_lshl_add_u64 v[208:209], s[46:47], 0, v[34:35]
	v_pk_mul_f32 v[16:17], v[14:15], v[188:189] op_sel_hi:[1,0] neg_lo:[0,1] neg_hi:[0,1]
	v_pk_mul_f32 v[14:15], v[12:13], v[188:189] op_sel_hi:[1,0] neg_lo:[0,1] neg_hi:[0,1]
	v_pk_mul_f32 v[12:13], v[10:11], v[188:189] op_sel_hi:[1,0] neg_lo:[0,1] neg_hi:[0,1]
	v_pk_mul_f32 v[10:11], v[8:9], v[188:189] op_sel_hi:[1,0] neg_lo:[0,1] neg_hi:[0,1]
	v_pk_mul_f32 v[8:9], v[6:7], v[188:189] op_sel_hi:[1,0] neg_lo:[0,1] neg_hi:[0,1]
	v_pk_mul_f32 v[6:7], v[4:5], v[188:189] op_sel_hi:[1,0] neg_lo:[0,1] neg_hi:[0,1]
	v_pk_mul_f32 v[4:5], v[2:3], v[188:189] op_sel_hi:[1,0] neg_lo:[0,1] neg_hi:[0,1]
	v_pk_mul_f32 v[2:3], v[20:21], v[188:189] op_sel_hi:[1,0] neg_lo:[0,1] neg_hi:[0,1]
	v_pk_add_f32 v[20:21], v[18:19], s[18:19] op_sel_hi:[0,1]
	s_mov_b32 s18, 0xc2600000
	v_add_u32_e32 v34, s13, v44
	s_mov_b32 s19, 0xc2640000
	v_add_u32_e32 v237, 0x780, v34
	v_add_u32_e32 v34, s13, v37
	s_lshl_b32 s8, s8, 2
	v_pk_add_f32 v[22:23], v[18:19], s[18:19] op_sel_hi:[0,1]
	s_mov_b32 s18, 0xc2480000
	v_add_u32_e32 v238, 0x780, v34
	s_sub_i32 s91, s8, s10
	v_add_u32_e32 v34, s11, v44
	s_add_i32 s8, s13, s9
	s_mov_b32 s19, 0xc24c0000
	v_add_u32_e32 v239, 0xffffff80, v34
	v_add_u32_e32 v34, s11, v37
	s_addk_i32 s8, 0x740
	v_pk_add_f32 v[24:25], v[18:19], s[18:19] op_sel_hi:[0,1]
	v_pk_add_f32 v[26:27], v[18:19], s[26:27] op_sel_hi:[0,1]
	v_pk_add_f32 v[28:29], v[18:19], s[14:15] op_sel_hi:[0,1]
	v_pk_add_f32 v[30:31], v[18:19], s[0:1] op_sel_hi:[0,1]
	v_pk_add_f32 v[32:33], v[18:19], s[16:17] op_sel_hi:[0,1]
	v_pk_add_f32 v[18:19], v[18:19], s[36:37] op_sel_hi:[0,1]
	v_add_u32_e32 v240, 0xffffff80, v34
	v_or_b32_e32 v34, s8, v185
	v_lshlrev_b32_e32 v36, 3, v189
	v_xor_b32_e32 v198, 0x80000000, v188
	v_and_b32_e32 v19, 0x7fffffff, v19
	v_and_b32_e32 v18, 0x7fffffff, v18
	v_and_b32_e32 v39, 0x7fffffff, v33
	v_and_b32_e32 v38, 0x7fffffff, v32
	v_and_b32_e32 v41, 0x7fffffff, v31
	v_and_b32_e32 v40, 0x7fffffff, v30
	v_and_b32_e32 v43, 0x7fffffff, v29
	v_and_b32_e32 v42, 0x7fffffff, v28
	v_and_b32_e32 v27, 0x7fffffff, v27
	v_and_b32_e32 v26, 0x7fffffff, v26
	v_and_b32_e32 v25, 0x7fffffff, v25
	v_and_b32_e32 v24, 0x7fffffff, v24
	v_and_b32_e32 v23, 0x7fffffff, v23
	v_and_b32_e32 v22, 0x7fffffff, v22
	v_and_b32_e32 v21, 0x7fffffff, v21
	v_and_b32_e32 v20, 0x7fffffff, v20
	s_lshl_b32 s90, s91, 14
	v_sub_u32_e32 v34, v34, v45
	s_mov_b32 s12, 0
	v_lshl_add_u64 v[194:195], v[192:193], 0, s[2:3]
	v_lshlrev_b32_e32 v229, 4, v189
	v_lshl_add_u32 v232, v185, 2, s33
	v_lshl_add_u32 v234, v44, 8, 0
	v_lshl_add_u64 v[204:205], v[202:203], 0, s[2:3]
	v_mov_b32_e32 v210, v198
	v_mov_b32_e32 v211, v198
	v_pk_mul_f32 v[32:33], v[20:21], v[188:189] op_sel_hi:[1,0] neg_lo:[0,1] neg_hi:[0,1]
	v_pk_mul_f32 v[30:31], v[22:23], v[188:189] op_sel_hi:[1,0] neg_lo:[0,1] neg_hi:[0,1]
	v_pk_mul_f32 v[28:29], v[24:25], v[188:189] op_sel_hi:[1,0] neg_lo:[0,1] neg_hi:[0,1]
	v_pk_mul_f32 v[26:27], v[26:27], v[188:189] op_sel_hi:[1,0] neg_lo:[0,1] neg_hi:[0,1]
	v_pk_mul_f32 v[24:25], v[42:43], v[188:189] op_sel_hi:[1,0] neg_lo:[0,1] neg_hi:[0,1]
	v_pk_mul_f32 v[22:23], v[40:41], v[188:189] op_sel_hi:[1,0] neg_lo:[0,1] neg_hi:[0,1]
	v_pk_mul_f32 v[20:21], v[38:39], v[188:189] op_sel_hi:[1,0] neg_lo:[0,1] neg_hi:[0,1]
	v_pk_mul_f32 v[18:19], v[18:19], v[188:189] op_sel_hi:[1,0] neg_lo:[0,1] neg_hi:[0,1]
	s_add_i32 s90, s90, 0x80000
	s_add_i32 s91, s91, 33
	v_subrev_u32_e32 v241, s11, v34
	s_mov_b64 s[8:9], -1
	v_lshlrev_b32_e32 v34, 1, v36
	s_branch .LBB0_306

.LBB0_480:
	s_or_b64 exec, exec, s[4:5]
	v_and_b32_e32 v20, 0xfffff0, v167
	v_lshlrev_b32_e32 v21, 1, v167
	v_and_or_b32 v20, v21, 8, v20
	v_lshrrev_b32_e32 v21, 1, v167
	v_and_b32_e32 v23, 3, v167
	v_and_or_b32 v21, v21, 4, v23
	v_add_u32_e32 v23, 32, v167
	v_and_b32_e32 v24, 0xfffff0, v23
	v_lshlrev_b32_e32 v23, 1, v23
	v_and_or_b32 v23, v23, 8, v24
	v_lshrrev_b32_e32 v20, 1, v20
	v_lshrrev_b32_e32 v22, 5, v168
	v_lshrrev_b32_e32 v23, 1, v23
	v_lshlrev_b32_e32 v18, 1, v168
	v_or_b32_e32 v20, v20, v22
	v_or_b32_e32 v22, v23, v22
	v_and_b32_e32 v19, 0xf0, v165
	v_lshlrev_b32_e32 v20, 9, v20
	v_lshlrev_b32_e32 v21, 6, v21
	v_lshlrev_b32_e32 v22, 9, v22
	v_lshlrev_b32_e32 v23, 8, v167
	v_and_b32_e32 v24, 48, v18
	v_or3_b32 v20, v20, v21, v24
	v_or3_b32 v21, v22, v21, v24
	v_bitop3_b32 v18, v18, v23, v19 bitop3:0xde
	v_add_u32_e32 v170, 0, v18
	v_add_u32_e32 v171, 0, v20
	v_add_u32_e32 v172, 0, v21
	s_waitcnt vmcnt(3)
	ds_write_b128 v170, v[2:5] offset:32768
	s_waitcnt vmcnt(1)
	ds_write_b128 v170, v[6:9] offset:40960
	ds_write_b128 v171, v[10:13]
	s_waitcnt vmcnt(0)
	ds_write_b128 v172, v[14:17]
	s_and_saveexec_b64 s[4:5], s[38:39]
	v_lshl_add_u32 v3, v165, 2, 0
	v_mul_f32_e32 v2, 0xbfb8aa3b, v169
	v_add_u32_e32 v3, 0x10000, v3
	ds_write_b32 v3, v2
	s_or_b64 exec, exec, s[4:5]
	s_lshl_b32 s7, s24, 6
	s_bitset1_b32 s7, 7
	v_add_u32_e32 v2, s7, v167
	v_ashrrev_i32_e32 v3, 31, v2
	v_lshlrev_b64 v[2:3], 8, v[2:3]
	v_lshl_or_b32 v2, v168, 1, v2
	v_lshl_add_u64 v[4:5], s[18:19], 0, v[2:3]
	s_movk_i32 s4, 0x2000
	v_add_co_u32_e32 v6, vcc, s4, v4
	v_lshl_add_u64 v[2:3], s[10:11], 0, v[2:3]
	s_nop 0
	v_addc_co_u32_e32 v7, vcc, 0, v5, vcc
	s_waitcnt lgkmcnt(0)
	s_barrier
	global_load_dwordx4 v[132:135], v[4:5], off
	global_load_dwordx4 v[136:139], v[6:7], off
	v_add_co_u32_e32 v4, vcc, 0x2000, v2
	s_nop 1
	v_addc_co_u32_e32 v5, vcc, 0, v3, vcc
	global_load_dwordx4 v[140:143], v[2:3], off
	global_load_dwordx4 v[144:147], v[4:5], off
	s_and_saveexec_b64 s[4:5], s[38:39]
	s_cbranch_execz .LBB0_484
	v_add_u32_e32 v2, s7, v165
	v_ashrrev_i32_e32 v3, 31, v2
	v_lshl_add_u64 v[2:3], v[2:3], 2, s[22:23]
	global_load_dword v169, v[2:3], off
.LBB0_484:
	s_or_b64 exec, exec, s[4:5]
	s_lshl_b32 s4, s25, 7
	v_and_b32_e32 v2, 63, v165
	v_writelane_b32 v255, s4, 57
	v_lshlrev_b32_e32 v4, 4, v2
	v_lshlrev_b32_e32 v3, 3, v2
	v_writelane_b32 v255, s5, 58
	s_and_b32 s4, s28, 0x3fffffc0
	v_and_b32_e32 v4, 0xc0, v4
	v_lshlrev_b32_e32 v5, 1, v2
	s_lshl_b32 s4, s4, 2
	v_and_or_b32 v4, v3, 24, v4
	v_and_b32_e32 v5, 32, v5
	v_and_b32_e32 v3, 0x100, v3
	s_add_i32 s35, s4, 0
	s_ashr_i32 s4, s33, 6
	v_or3_b32 v3, v4, v5, v3
	s_sub_i32 s25, s6, s4
	v_lshlrev_b32_e32 v5, 4, v1
	s_movk_i32 s6, 0xf0
	v_and_b32_e32 v6, 0xf0, v5
	v_bitop3_b32 v176, v34, v5, s6 bitop3:0x78
	s_movk_i32 s6, 0x60
	v_bitop3_b32 v179, v34, v6, s6 bitop3:0x36
	s_movk_i32 s6, 0x80
	v_bitop3_b32 v185, v34, v6, s6 bitop3:0x36
	s_movk_i32 s6, 0xa0
	v_bitop3_b32 v186, v34, v6, s6 bitop3:0x36
	s_movk_i32 s6, 0xc0
	v_bitop3_b32 v187, v34, v6, s6 bitop3:0x36
	s_movk_i32 s6, 0xe0
	s_add_i32 s5, 0, 0x10000
	v_bitop3_b32 v188, v34, v6, s6 bitop3:0x36
	v_cmp_gt_u32_e64 s[40:41], 32, v2
	v_lshlrev_b32_e32 v2, 2, v165
	v_readlane_b32 s6, v255, 27
	s_addk_i32 s9, 0xff40
	v_lshlrev_b32_e32 v4, 2, v166
	v_add_u32_e32 v174, s5, v34
	v_add_u32_e32 v189, s6, v2
	v_add_u32_e32 v190, s6, v34
	s_add_i32 s6, 0, 0x4000
	v_add_u32_e32 v192, s5, v2
	s_lshl_b32 s5, s8, 2
	v_add_u32_e32 v2, s9, v1
	v_mov_b32_e32 v16, v35
	v_mov_b32_e32 v17, v35
	v_add_u32_e32 v173, 0, v3
	s_add_i32 s35, s35, 0x10200
	v_bitop3_b32 v177, v34, v6, 32 bitop3:0x36
	v_bitop3_b32 v178, v34, v6, 64 bitop3:0x36
	v_add_u32_e32 v191, s6, v3
	s_sub_i32 s12, s4, s5
	v_sub_u32_e32 v193, v2, v4
	s_lshl_b32 s4, s8, 8
	v_mov_b32_e32 v2, v35
	v_mov_b32_e32 v3, v35
	v_mov_b32_e32 v4, v35
	v_mov_b32_e32 v5, v35
	v_mov_b32_e32 v6, v35
	v_mov_b32_e32 v7, v35
	v_mov_b32_e32 v8, v35
	v_mov_b32_e32 v9, v35
	v_mov_b32_e32 v10, v35
	v_mov_b32_e32 v11, v35
	v_mov_b32_e32 v12, v35
	v_mov_b32_e32 v13, v35
	v_mov_b32_e32 v14, v35
	v_mov_b32_e32 v15, v35
	v_mov_b64_e32 v[32:33], v[16:17]
	v_mov_b64_e32 v[50:51], v[16:17]
	v_mov_b64_e32 v[66:67], v[16:17]
	s_add_i32 s34, s24, 4
	v_lshl_add_u32 v175, v1, 8, 0
	v_lshl_add_u32 v184, v1, 2, s35
	s_add_i32 s13, s4, 0x7ff
	s_mov_b32 s30, 0
	v_mov_b32_e32 v194, 0
	v_mov_b64_e32 v[30:31], v[14:15]
	v_mov_b64_e32 v[28:29], v[12:13]
	v_mov_b64_e32 v[26:27], v[10:11]
	v_mov_b64_e32 v[24:25], v[8:9]
	v_mov_b64_e32 v[22:23], v[6:7]
	v_mov_b64_e32 v[20:21], v[4:5]
	v_mov_b64_e32 v[18:19], v[2:3]
	v_mov_b64_e32 v[48:49], v[14:15]
	v_mov_b64_e32 v[46:47], v[12:13]
	v_mov_b64_e32 v[44:45], v[10:11]
	v_mov_b64_e32 v[42:43], v[8:9]
	v_mov_b64_e32 v[40:41], v[6:7]
	v_mov_b64_e32 v[38:39], v[4:5]
	v_mov_b64_e32 v[36:37], v[2:3]
	v_mov_b64_e32 v[64:65], v[14:15]
	v_mov_b64_e32 v[62:63], v[12:13]
	v_mov_b64_e32 v[60:61], v[10:11]
	v_mov_b64_e32 v[58:59], v[8:9]
	v_mov_b64_e32 v[56:57], v[6:7]
	v_mov_b64_e32 v[54:55], v[4:5]
	v_mov_b64_e32 v[52:53], v[2:3]
	v_mov_b32_e32 v196, 0

.LBB0_656:
	s_or_b64 exec, exec, s[4:5]
	v_readlane_b32 s4, v255, 24
	s_waitcnt lgkmcnt(0)
	s_barrier
	v_mov_b32_e32 v1, s4
	ds_read_b32 v1, v1
	s_mov_b64 s[4:5], -1
	s_waitcnt lgkmcnt(0)
	s_barrier
	v_readfirstlane_b32 s8, v1
	s_cmpk_gt_i32 s8, 0x5f
	s_cbranch_scc1 .LBB0_651
	s_mul_hi_i32 s4, s8, 0xd5555555
	s_lshr_b32 s5, s4, 31
	s_ashr_i32 s21, s4, 1
	s_mul_hi_i32 s4, s8, 0x2aaaaaab
	s_add_i32 s21, s21, s5
	s_lshr_b32 s5, s4, 31
	s_lshr_b32 s4, s4, 1
	s_add_i32 s4, s4, s5
	s_mul_i32 s4, s4, 12
	s_sub_i32 s4, s8, s4
	s_lshl_b32 s4, s4, 3
	s_or_b32 s4, s4, s52
	s_mul_hi_i32 s5, s4, 0x2aaaaaab
	s_lshr_b32 s8, s5, 31
	s_add_i32 s12, s5, s8
	s_mul_i32 s5, s12, 6
	v_mov_b32_e32 v1, v0
	s_sub_i32 s4, s4, s5
	s_add_i32 s20, s21, 7
	v_readfirstlane_b32 s5, v1
	s_ashr_i32 s25, s5, 6
	s_lshl_b32 s5, s20, 8
	s_lshl_b32 s28, s25, 5
	s_ashr_i32 s13, s12, 31
	s_lshl_b32 s18, s4, 23
	s_add_i32 s9, s28, s5
	s_lshl_b64 s[10:11], s[12:13], 11
	s_lshl_b32 s8, s4, 7
	s_add_i32 s5, s18, 0x6000000
	v_readlane_b32 s30, v254, 52
	v_readlane_b32 s31, v254, 53
	s_add_u32 s22, s30, s5
	s_addc_u32 s23, s31, 0
	s_bfe_i64 s[4:5], s[4:5], 0x100000
	s_lshl_b64 s[4:5], s[4:5], 23
	s_add_u32 s4, s30, s4
	s_addc_u32 s5, s31, s5
	s_add_i32 s18, s18, 0x3000000
	s_add_u32 s18, s30, s18
	s_addc_u32 s19, s31, 0
	s_lshl_b64 s[12:13], s[12:13], 19
	s_add_u32 s18, s18, s12
	s_addc_u32 s19, s19, s13
	s_add_u32 s22, s22, s12
	s_addc_u32 s23, s23, s13
	s_lshl_b32 s13, s20, 2
	v_ashrrev_i32_e32 v163, 4, v1
	s_or_b32 s12, s13, 3
	v_lshlrev_b32_e32 v8, 3, v1
	v_lshl_add_u32 v2, s12, 6, v163
	v_and_b32_e32 v162, 0x78, v8
	v_ashrrev_i32_e32 v3, 31, v2
	v_lshlrev_b32_e32 v9, 1, v162
	v_lshlrev_b64 v[2:3], 8, v[2:3]
	v_or_b32_e32 v2, v2, v9
	v_lshl_add_u64 v[4:5], s[18:19], 0, v[2:3]
	s_movk_i32 s20, 0x2000
	v_add_co_u32_e32 v6, vcc, s20, v4
	v_lshl_add_u64 v[2:3], s[22:23], 0, v[2:3]
	s_nop 0
	v_addc_co_u32_e32 v7, vcc, 0, v5, vcc
	global_load_dwordx4 v[114:117], v[4:5], off
	global_load_dwordx4 v[118:121], v[6:7], off
	global_load_dwordx4 v[150:153], v[2:3], off
	v_add_co_u32_e32 v2, vcc, s20, v2
	v_and_b32_e32 v186, 31, v1
	s_nop 0
	v_addc_co_u32_e32 v3, vcc, 0, v3, vcc
	global_load_dwordx4 v[158:161], v[2:3], off
	v_or_b32_e32 v2, s9, v186
	v_ashrrev_i32_e32 v3, 31, v2
	v_lshl_add_u64 v[2:3], s[10:11], 0, v[2:3]
	v_bfe_u32 v187, v1, 5, 1
	v_lshlrev_b64 v[2:3], 8, v[2:3]
	v_lshl_add_u64 v[2:3], s[4:5], 0, v[2:3]
	v_lshlrev_b32_e32 v34, 4, v187
	v_lshl_add_u64 v[2:3], v[2:3], 0, v[34:35]
	global_load_dwordx4 v[122:125], v[2:3], off
	global_load_dwordx4 v[126:129], v[2:3], off offset:32
	global_load_dwordx4 v[130:133], v[2:3], off offset:64
	global_load_dwordx4 v[134:137], v[2:3], off offset:96
	global_load_dwordx4 v[138:141], v[2:3], off offset:128
	global_load_dwordx4 v[142:145], v[2:3], off offset:160
	global_load_dwordx4 v[146:149], v[2:3], off offset:192
	global_load_dwordx4 v[154:157], v[2:3], off offset:224
	v_and_b32_e32 v6, 0xfffff0, v163
	v_lshlrev_b32_e32 v7, 1, v163
	v_and_or_b32 v6, v7, 8, v6
	v_lshrrev_b32_e32 v7, 1, v163
	v_lshrrev_b32_e32 v6, 1, v6
	v_bfe_u32 v10, v8, 5, 2
	v_and_b32_e32 v3, 3, v163
	s_movk_i32 s5, 0xf0
	v_or_b32_e32 v6, v6, v10
	v_and_or_b32 v3, v7, 4, v3
	v_add_u32_e32 v7, 32, v163
	v_bitop3_b32 v5, v9, v1, s5 bitop3:0x78
	v_lshlrev_b32_e32 v2, 9, v6
	v_and_b32_e32 v6, 48, v9
	v_and_b32_e32 v9, 0xfffff0, v7
	v_lshlrev_b32_e32 v7, 1, v7
	v_and_or_b32 v7, v7, 8, v9
	v_lshrrev_b32_e32 v7, 1, v7
	v_lshlrev_b32_e32 v3, 6, v3
	v_or_b32_e32 v7, v7, v10
	v_lshlrev_b32_e32 v7, 9, v7
	v_lshlrev_b32_e32 v10, 8, v163
	v_or3_b32 v189, v2, v3, v6
	v_or3_b32 v188, v7, v3, v6
	v_add3_u32 v190, 0, v5, v10
	v_add_u32_e32 v5, 0, v189
	v_lshlrev_b32_e32 v7, 4, v1
	s_lshl_b32 s4, s25, 2
	s_add_i32 s25, s4, 0
	s_movk_i32 s4, 0x60
	v_lshlrev_b32_e32 v9, 1, v1
	v_and_b32_e32 v3, 32, v9
	v_and_b32_e32 v4, 63, v1
	v_and_b32_e32 v2, 0xc0, v7
	s_waitcnt vmcnt(11)
	ds_write_b128 v190, v[114:117] offset:32768
	s_waitcnt vmcnt(10)
	ds_write_b128 v190, v[118:121] offset:40960
	s_waitcnt vmcnt(9)
	ds_write_b128 v5, v[150:153]
	v_add_u32_e32 v5, 0, v188
	s_addk_i32 s28, 0xff40
	v_bitop3_b32 v192, v34, v7, s5 bitop3:0x78
	v_cmp_gt_u32_e64 s[38:39], 32, v4
	v_cmp_eq_u32_e64 s[40:41], 0, v4
	s_waitcnt vmcnt(8)
	ds_write_b128 v5, v[158:161]
	v_and_b32_e32 v5, 0xf0, v7
	v_bitop3_b32 v195, v34, v5, s4 bitop3:0x36
	s_movk_i32 s4, 0x80
	v_bitop3_b32 v196, v34, v5, s4 bitop3:0x36
	s_movk_i32 s4, 0xa0
	v_bitop3_b32 v197, v34, v5, s4 bitop3:0x36
	s_movk_i32 s4, 0xc0
	v_bitop3_b32 v198, v34, v5, s4 bitop3:0x36
	s_movk_i32 s4, 0xe0
	v_bitop3_b32 v199, v34, v5, s4 bitop3:0x36
	s_movk_i32 s4, 0x118
	v_and_or_b32 v3, v8, s4, v3
	v_bitop3_b32 v193, v34, v5, 32 bitop3:0x36
	v_bitop3_b32 v194, v34, v5, 64 bitop3:0x36
	v_lshlrev_b32_e32 v4, 2, v187
	v_add3_u32 v200, v2, 0, v3
	v_or_b32_e32 v2, s28, v186
	v_mov_b32_e32 v34, v35
	v_mov_b32_e32 v48, v35
	v_mov_b32_e32 v49, v35
	v_sub_u32_e32 v201, v2, v4
	s_lshl_b32 s4, s21, 8
	s_lshl_b32 s31, s21, 2
	v_mov_b32_e32 v36, v35
	v_mov_b32_e32 v37, v35
	v_mov_b32_e32 v38, v35
	v_mov_b32_e32 v39, v35
	v_mov_b32_e32 v40, v35
	v_mov_b32_e32 v41, v35
	v_mov_b32_e32 v42, v35
	v_mov_b32_e32 v43, v35
	v_mov_b32_e32 v44, v35
	v_mov_b32_e32 v45, v35
	v_mov_b32_e32 v46, v35
	v_mov_b32_e32 v47, v35
	v_mov_b64_e32 v[2:3], v[34:35]
	v_mov_b64_e32 v[18:19], v[34:35]
	v_mov_b64_e32 v[64:65], v[48:49]
	v_mov_b64_e32 v[80:81], v[48:49]
	s_add_i32 s13, s13, 4
	s_ashr_i32 s24, s9, 6
	s_mov_b32 s20, 0
	s_add_i32 s25, s25, 0x10a00
	v_lshl_add_u32 v191, v186, 8, 0
	s_add_i32 s34, s4, 0x7ff
	s_add_i32 s30, s31, 31
	s_add_i32 s31, s31, 32
	v_mov_b32_e32 v202, 0
	s_mov_b64 s[4:5], 0
	v_mov_b64_e32 v[4:5], v[36:37]
	v_mov_b64_e32 v[6:7], v[38:39]
	v_mov_b64_e32 v[8:9], v[40:41]
	v_mov_b64_e32 v[10:11], v[42:43]
	v_mov_b64_e32 v[12:13], v[44:45]
	v_mov_b64_e32 v[14:15], v[46:47]
	v_mov_b64_e32 v[16:17], v[48:49]
	v_mov_b64_e32 v[20:21], v[36:37]
	v_mov_b64_e32 v[22:23], v[38:39]
	v_mov_b64_e32 v[24:25], v[40:41]
	v_mov_b64_e32 v[26:27], v[42:43]
	v_mov_b64_e32 v[28:29], v[44:45]
	v_mov_b64_e32 v[30:31], v[46:47]
	v_mov_b64_e32 v[32:33], v[48:49]
	v_mov_b64_e32 v[62:63], v[46:47]
	v_mov_b64_e32 v[60:61], v[44:45]
	v_mov_b64_e32 v[58:59], v[42:43]
	v_mov_b64_e32 v[56:57], v[40:41]
	v_mov_b64_e32 v[54:55], v[38:39]
	v_mov_b64_e32 v[52:53], v[36:37]
	v_mov_b64_e32 v[50:51], v[34:35]
	v_mov_b64_e32 v[78:79], v[46:47]
	v_mov_b64_e32 v[76:77], v[44:45]
	v_mov_b64_e32 v[74:75], v[42:43]
	v_mov_b64_e32 v[72:73], v[40:41]
	v_mov_b64_e32 v[70:71], v[38:39]
	v_mov_b64_e32 v[68:69], v[36:37]
	v_mov_b64_e32 v[66:67], v[34:35]
	s_waitcnt lgkmcnt(0)
	s_barrier
	s_cmp_eq_u32 s31, s20
	s_cbranch_scc1 .LBB0_665
